# P7 start stagger in 4 groups (bi&3) x 3 sleeps instead of 2 groups x 7 sleeps
# speedup vs baseline: 1.0158x; 1.0158x over previous
.LBB0_295:
	s_nop 0
	v_readlane_b32 s0, v254, 37
	v_readlane_b32 s1, v254, 38
	s_and_b64 vcc, exec, s[0:1]
	s_cbranch_vccz .LBB0_316
	s_mov_b32 s36, s35
	s_mov_b32 s0, s98
	s_mov_b32 s1, -1
	v_mbcnt_lo_u32_b32 v0, -1, 0
	v_mbcnt_hi_u32_b32 v0, s1, v0
	v_readlane_b32 s1, v252, 0
	v_lshl_add_u32 v158, s0, 6, v0
	s_mov_b32 s4, s1
	s_ashr_i32 s0, s1, 3
	v_readlane_b32 s5, v254, 6
	s_cmp_ge_i32 s0, s5
	s_cbranch_scc1 .LBB0_315
	s_cmpk_gt_i32 s0, 0x9f
	s_cbranch_scc1 .LBB0_315
	s_and_b32 s6, s0, 3
.Lp7_stag_loop:
	s_cmp_eq_u32 s6, 0
	s_cbranch_scc1 .Lp7_nostag
	s_sleep 127
	s_sleep 127
	s_sleep 127
	s_add_i32 s6, s6, -1
	s_branch .Lp7_stag_loop
